# grid barrier: workgroups arriving with 1 or 6 workgroups of their XCD still missing issue an extra L2 write-back while they wait, so the last arriver's release write-back is short
# baseline (speedup 1.0000x reference)
.LBB0_139:
	v_readlane_b32 s2, v254, 52
	s_lshl_b32 s88, s2, 6
	s_lshl_b64 s[4:5], s[88:89], 2
	s_add_u32 s4, s28, s4
	s_addc_u32 s5, s29, s5
	v_mov_b32_e32 v0, 0x1000
	v_mov_b32_e32 v4, 1
	global_atomic_add v4, v0, v4, s[4:5] offset:1024 sc0
	v_cvt_f32_u32_e32 v0, v3
	v_sub_u32_e32 v5, 0, v3
	v_rcp_iflag_f32_e32 v0, v0
	s_nop 0
	v_mul_f32_e32 v0, 0x4f7ffffe, v0
	v_cvt_u32_f32_e32 v0, v0
	v_mul_lo_u32 v5, v5, v0
	v_mul_hi_u32 v5, v0, v5
	v_add_u32_e32 v0, v0, v5
	s_waitcnt vmcnt(0)
	v_mul_hi_u32 v0, v4, v0
	v_mul_lo_u32 v5, v0, v3
	v_sub_u32_e32 v5, v4, v5
	v_add_u32_e32 v6, 1, v0
	v_cmp_ge_u32_e32 vcc, v5, v3
	v_add_u32_e32 v4, 1, v4
	s_nop 0
	v_cndmask_b32_e32 v0, v0, v6, vcc
	v_sub_u32_e32 v6, v5, v3
	v_cndmask_b32_e32 v5, v5, v6, vcc
	v_add_u32_e32 v6, 1, v0
	v_cmp_ge_u32_e32 vcc, v5, v3
	s_nop 1
	v_cndmask_b32_e32 v0, v0, v6, vcc
	v_mul_lo_u32 v5, v3, v0
	v_add_u32_e32 v3, v5, v3
	v_cmp_ne_u32_e32 vcc, v4, v3
	s_and_saveexec_b64 s[6:7], vcc
	s_xor_b64 s[6:7], exec, s[6:7]
	s_cbranch_execz .LBB0_153
	s_waitcnt lgkmcnt(0)
	v_sub_u32_e32 v2, v3, v4
	v_cmp_eq_u32_e32 vcc, 1, v2
	s_cbranch_vccnz .Lpf1_do
	v_cmp_eq_u32_e32 vcc, 6, v2
	s_cbranch_vccnz .Lpf1_do
	s_branch .Lpf1_skip
.Lpf1_do:
	buffer_wbl2 sc1
.Lpf1_skip:
	v_mov_b32_e32 v2, 0x2000
	global_load_dword v2, v2, s[4:5] offset:1024 sc1
	s_add_u32 s10, s4, 0x2400
	s_addc_u32 s11, s5, 0
	s_waitcnt vmcnt(0)
	v_cmp_eq_u32_e32 vcc, v2, v0
	s_and_saveexec_b64 s[8:9], vcc
	s_cbranch_execz .LBB0_152
	s_mov_b32 s2, 1
	s_mov_b64 s[12:13], 0
	s_branch .LBB0_143

.LBB0_303:
	v_readlane_b32 s2, v254, 52
	s_lshl_b32 s88, s2, 6
	s_lshl_b64 s[4:5], s[88:89], 2
	s_add_u32 s6, s28, s4
	s_addc_u32 s7, s29, s5
	v_mov_b32_e32 v0, 0x1000
	v_mov_b32_e32 v4, 1
	global_atomic_add v4, v0, v4, s[6:7] offset:1024 sc0
	v_cvt_f32_u32_e32 v0, v3
	v_sub_u32_e32 v5, 0, v3
	v_rcp_iflag_f32_e32 v0, v0
	s_nop 0
	v_mul_f32_e32 v0, 0x4f7ffffe, v0
	v_cvt_u32_f32_e32 v0, v0
	v_mul_lo_u32 v5, v5, v0
	v_mul_hi_u32 v5, v0, v5
	v_add_u32_e32 v0, v0, v5
	s_waitcnt vmcnt(0)
	v_mul_hi_u32 v0, v4, v0
	v_mul_lo_u32 v5, v0, v3
	v_sub_u32_e32 v5, v4, v5
	v_add_u32_e32 v6, 1, v0
	v_cmp_ge_u32_e32 vcc, v5, v3
	v_add_u32_e32 v4, 1, v4
	s_nop 0
	v_cndmask_b32_e32 v0, v0, v6, vcc
	v_sub_u32_e32 v6, v5, v3
	v_cndmask_b32_e32 v5, v5, v6, vcc
	v_add_u32_e32 v6, 1, v0
	v_cmp_ge_u32_e32 vcc, v5, v3
	s_nop 1
	v_cndmask_b32_e32 v0, v0, v6, vcc
	v_mul_lo_u32 v5, v3, v0
	v_add_u32_e32 v3, v5, v3
	v_cmp_ne_u32_e32 vcc, v4, v3
	s_and_saveexec_b64 s[4:5], vcc
	s_xor_b64 s[4:5], exec, s[4:5]
	s_cbranch_execz .LBB0_317
	s_waitcnt lgkmcnt(0)
	v_sub_u32_e32 v2, v3, v4
	v_cmp_eq_u32_e32 vcc, 1, v2
	s_cbranch_vccnz .Lpf3_do
	v_cmp_eq_u32_e32 vcc, 6, v2
	s_cbranch_vccnz .Lpf3_do
	s_branch .Lpf3_skip

.Lpf3_skip:
	v_mov_b32_e32 v2, 0x2000
	global_load_dword v2, v2, s[6:7] offset:1024 sc1
	s_add_u32 s10, s6, 0x2400
	s_addc_u32 s11, s7, 0
	s_waitcnt vmcnt(0)
	v_cmp_eq_u32_e32 vcc, v2, v0
	s_and_saveexec_b64 s[8:9], vcc
	s_cbranch_execz .LBB0_316
	s_mov_b32 s2, 1
	s_mov_b64 s[12:13], 0
	s_branch .LBB0_307

.LBB0_1523:
	v_readlane_b32 s2, v254, 52
	s_lshl_b32 s88, s2, 6
	s_lshl_b64 s[4:5], s[88:89], 2
	s_add_u32 s8, s28, s4
	s_addc_u32 s9, s29, s5
	v_mov_b32_e32 v0, 0x1000
	v_mov_b32_e32 v4, 1
	global_atomic_add v4, v0, v4, s[8:9] offset:1024 sc0
	v_cvt_f32_u32_e32 v0, v3
	v_sub_u32_e32 v5, 0, v3
	v_rcp_iflag_f32_e32 v0, v0
	s_nop 0
	v_mul_f32_e32 v0, 0x4f7ffffe, v0
	v_cvt_u32_f32_e32 v0, v0
	v_mul_lo_u32 v5, v5, v0
	v_mul_hi_u32 v5, v0, v5
	v_add_u32_e32 v0, v0, v5
	s_waitcnt vmcnt(0)
	v_mul_hi_u32 v0, v4, v0
	v_mul_lo_u32 v5, v0, v3
	v_sub_u32_e32 v5, v4, v5
	v_add_u32_e32 v6, 1, v0
	v_cmp_ge_u32_e32 vcc, v5, v3
	v_add_u32_e32 v4, 1, v4
	s_nop 0
	v_cndmask_b32_e32 v0, v0, v6, vcc
	v_sub_u32_e32 v6, v5, v3
	v_cndmask_b32_e32 v5, v5, v6, vcc
	v_add_u32_e32 v6, 1, v0
	v_cmp_ge_u32_e32 vcc, v5, v3
	s_nop 1
	v_cndmask_b32_e32 v0, v0, v6, vcc
	v_mul_lo_u32 v5, v3, v0
	v_add_u32_e32 v3, v5, v3
	v_cmp_ne_u32_e32 vcc, v4, v3
	s_and_saveexec_b64 s[4:5], vcc
	s_xor_b64 s[4:5], exec, s[4:5]
	s_cbranch_execz .LBB0_1537
	s_waitcnt lgkmcnt(0)
	v_sub_u32_e32 v2, v3, v4
	v_cmp_eq_u32_e32 vcc, 1, v2
	s_cbranch_vccnz .Lpf14_do
	v_cmp_eq_u32_e32 vcc, 6, v2
	s_cbranch_vccnz .Lpf14_do
	s_branch .Lpf14_skip

.Lpf14_skip:
	v_mov_b32_e32 v2, 0x2000
	global_load_dword v2, v2, s[8:9] offset:1024 sc1
	s_add_u32 s12, s8, 0x2400
	s_addc_u32 s13, s9, 0
	s_waitcnt vmcnt(0)
	v_cmp_eq_u32_e32 vcc, v2, v0
	s_and_saveexec_b64 s[10:11], vcc
	s_cbranch_execz .LBB0_1536
	s_mov_b32 s2, 1
	s_mov_b64 s[14:15], 0
	s_branch .LBB0_1527
